# baseline (speedup 1.0000x reference)
;   const int tid = tidx, lane = tid & 63, w = tid >> 6;
;   const int wm = w >> 1, wn = w & 1;
;   const int l15 = lane & 15, quad = lane >> 4;
;   constexpr int NB = (TN * 32 * 8) / NT;
;   constexpr int BUFE = (256 + (TN > 4 ? 192 : 128)) * GSTR;
;   u32x4 ra0[4], ra1[4];
;   u32x4 rb0[NB], rb1[NB];
;   const int cr = tid >> 3, ck = tid & 7;
;   const unsigned aoffb = (unsigned)(cr * lda + ck * 8) * 2u;
;   const unsigned boffb = (unsigned)(cr * ldb + ck * 8) * 2u;
.LBB0_386:
	s_andn2_b64 vcc, exec, s[10:11]
	s_cbranch_vccnz .LBB0_392
	s_waitcnt vmcnt(14)
	v_ashrrev_i32_e32 v10, 3, v150
	s_movk_i32 s0, 0x1d00
	v_lshlrev_b32_e32 v3, 3, v150
	v_mul_lo_u32 v0, v10, s0
	v_and_b32_e32 v2, 56, v3
	v_ashrrev_i32_e32 v11, 1, v150
	v_or_b32_e32 v0, v0, v2
	s_waitcnt vmcnt(8)
	v_lshlrev_b32_e32 v15, 1, v2
	v_and_b32_e32 v2, 15, v150
	v_and_b32_e32 v19, 0xffffffc0, v11
	s_movk_i32 s5, 0xa0
	v_or_b32_e32 v12, v19, v2
	v_mul_lo_u32 v12, v12, s5
	s_add_i32 s0, 0, 0xf000
	v_add_u32_e32 v18, s0, v12
	v_readlane_b32 s0, v254, 12
	v_and_b32_e32 v20, 0x4f, v150
	s_waitcnt vmcnt(11)
	v_add_u32_e32 v28, 0x1400, v18
	v_add_u32_e32 v29, 0x1e00, v18
	v_mov_b32_e32 v18, s0
	s_waitcnt lgkmcnt(0)
	v_lshl_or_b32 v8, v10, 8, v15
	v_mul_lo_u32 v16, v10, s5
	v_and_b32_e32 v10, 48, v150
	v_mul_u32_u24_e32 v13, 0xa0, v20
	v_mad_u32_u24 v25, v20, s5, 0
	v_mad_u32_u24 v18, v20, s5, v18
	v_lshrrev_b32_e32 v20, 2, v150
	v_add_u32_e32 v23, 0, v15
	v_add_u32_e32 v11, 0, v10
	v_lshrrev_b32_e32 v17, 3, v150
	v_and_b32_e32 v9, 4, v17
	v_lshlrev_b32_e32 v9, 2, v9
	v_and_or_b32 v9, v17, 35, v9
	v_and_b32_e32 v17, 24, v17
	v_lshrrev_b32_e32 v17, 1, v17
	v_or_b32_e32 v17, v9, v17
	v_mul_u32_u24_e32 v17, 0xa0, v17
	v_add_u32_e32 v15, 0xa000, v15
	v_add_u32_e32 v15, v15, v17
	v_add_u32_e32 v26, s0, v10
	v_and_or_b32 v19, v20, 12, v19
	v_and_b32_e32 v20, 64, v150
	s_movk_i32 s0, 0x110
	v_add_u32_e32 v22, 0x5000, v16
	v_add_u32_e32 v24, 0x7800, v16
	v_add_u32_e32 v21, 0, v12
	v_add_u32_e32 v14, v23, v16
	v_add_u32_e32 v27, 0xf000, v11
	v_add_u32_e32 v30, 0xa00, v18
	v_add_u32_e32 v31, 0x1400, v18
	v_add_u32_e32 v32, 0x1e00, v18
	v_lshl_add_u32 v20, v20, 1, 0
	v_lshlrev_b32_e32 v33, 1, v2
	v_mul_lo_u32 v19, v19, s0
	v_lshlrev_b32_e32 v0, 1, v0
	v_mov_b32_e32 v9, v1
	v_add_u32_e32 v16, 0x2800, v14
	v_add_u32_e32 v17, 0x2800, v15
	v_add3_u32 v19, v20, v33, v19
	v_cmp_gt_i32_e32 vcc, s36, v150
	v_add_u32_e32 v20, v21, v10
	v_add_u32_e32 v21, v25, v10
	v_add_u32_e32 v22, v23, v22
	v_add_u32_e32 v23, v23, v24
	v_add_u32_e32 v24, v27, v12
	v_add_u32_e32 v25, v26, v13
	v_add_u32_e32 v26, v28, v10
	v_add_u32_e32 v27, v29, v10
	v_add_u32_e32 v28, v30, v10
	v_add_u32_e32 v29, v31, v10
	v_add_u32_e32 v30, v32, v10
	v_readlane_b32 s0, v251, 0
	s_branch .LBB0_389

;     ...
;   G_LOAD(ra0, rb0, 0);
;   G_LOAD(ra1, rb1, 64);
;   __syncthreads();
;   G_STORE(ra0, rb0, 0);
;   __syncthreads();
;   G_READ(fa0, fb0, 0, 0);
; #pragma unroll
;   for (int k0 = 0; k0 < K; k0 += 128) {
;     G_READ(fa1, fb1, 0, 32);
;     if (k0 + 128 < K) G_LOAD(ra0, rb0, k0 + 128);
;     __builtin_amdgcn_sched_barrier(0);
;     G_MFMA_ST(fa0, fb0, ra1, rb1, 1);
;     __syncthreads();
;     G_READ(fa0, fb0, 1, 0);
;     __builtin_amdgcn_sched_barrier(0);
;     G_MFMA(fa1, fb1);
; __device__ __forceinline__ void phase_mlstm_qkv(const Params& p, const int tidx) {
;     ...
;   for (int tile = blockIdx.x; tile < 128 * 12; tile += gridDim.x) {
;     int mt = tile / 12, mh = tile % 12;
;     int which = mh >> 2, h = mh & 3;
;     const bf16_t* A;
;     int lda;
;     if (which < 2) { A = XC + (size_t)mt * 256 * NP + h * 128; lda = NP; }
;     else { A = P + (size_t)mt * 256 * NP + OFF_AX + h * 128; lda = NP; }
;     f32x4 acc[4][4];
;     zero_acc<4>(acc);
;     gemm_main<4, 128>(acc, A, lda, W + (size_t)mh * 16384, 128, sA, sB, tidx);
.LBB0_389:
	s_mul_hi_i32 s10, s0, 0x2aaaaaab
	s_lshr_b32 s11, s10, 31
	s_ashr_i32 s10, s10, 1
	s_add_i32 s12, s10, s11
	s_mul_i32 s10, s12, 12
	s_sub_i32 s10, s0, s10
	s_lshl_b32 s11, s10, 7
	s_ashr_i32 s14, s10, 2
	s_and_b32 s11, s11, 0x180
	s_cmp_lt_i32 s14, 2
	s_cselect_b32 s16, 0x1800, 0
	s_add_u32 s16, s94, s16
	s_mul_i32 s15, s12, 0x3a0000
	s_addc_u32 s17, s95, 0
	s_mul_hi_i32 s13, s12, 0x3a0000
	s_add_u32 s15, s16, s15
	s_addc_u32 s13, s17, s13
	s_lshl_b32 s18, s11, 1
	s_add_u32 s16, s15, s18
	s_addc_u32 s17, s13, 0
	s_ashr_i32 s11, s10, 31
	s_lshl_b64 s[10:11], s[10:11], 15
	s_add_u32 s20, s19, s10
	v_lshl_add_u64 v[56:57], s[16:17], 0, v[0:1]
	s_mov_b32 s5, 0xe8000
	s_addc_u32 s21, s22, s11
	v_add_co_u32_e64 v60, s[10:11], s5, v56
	s_mov_b32 s5, 0x1d0000
	s_nop 0
	v_addc_co_u32_e64 v61, s[10:11], 0, v57, s[10:11]
	v_add_co_u32_e64 v64, s[10:11], s5, v56
	global_load_dwordx4 v[32:35], v[56:57], off
	global_load_dwordx4 v[36:39], v[60:61], off
	v_addc_co_u32_e64 v65, s[10:11], 0, v57, s[10:11]
	s_mov_b32 s5, 0x2b8000
	v_add_co_u32_e64 v68, s[10:11], s5, v56
	global_load_dwordx4 v[40:43], v[64:65], off
	s_nop 0
	v_addc_co_u32_e64 v69, s[10:11], 0, v57, s[10:11]
	global_load_dwordx4 v[44:47], v[68:69], off
	v_lshl_add_u64 v[72:73], s[20:21], 0, v[8:9]
	s_movk_i32 s10, 0x4000
	global_load_dwordx4 v[48:51], v[72:73], off
	v_add_co_u32_e64 v76, s[10:11], s10, v72
	v_add_u32_e32 v31, v11, v12
	s_nop 0
	v_addc_co_u32_e64 v77, s[10:11], 0, v73, s[10:11]
	global_load_dwordx4 v[52:55], v[76:77], off
	s_nop 0
	global_load_dwordx4 v[56:59], v[56:57], off offset:128
	s_nop 0
	global_load_dwordx4 v[60:63], v[60:61], off offset:128
	s_nop 0
	global_load_dwordx4 v[64:67], v[64:65], off offset:128
	s_nop 0
	global_load_dwordx4 v[68:71], v[68:69], off offset:128
	s_nop 0
	global_load_dwordx4 v[72:75], v[72:73], off offset:128
	s_nop 0
	global_load_dwordx4 v[76:79], v[76:77], off offset:128
	v_add_u32_e32 v84, v11, v13
	s_barrier
	s_waitcnt vmcnt(11)
	ds_write_b128 v14, v[32:35]
	s_waitcnt vmcnt(10)
	ds_write_b128 v14, v[36:39] offset:10240
	s_waitcnt vmcnt(9)
	ds_write_b128 v14, v[40:43] offset:20480
	s_waitcnt vmcnt(8)
	ds_write_b128 v14, v[44:47] offset:30720
	s_waitcnt vmcnt(7)
	ds_write_b128 v15, v[48:51]
	s_waitcnt vmcnt(6)
	ds_write_b128 v17, v[52:55]
	s_waitcnt lgkmcnt(0)
	s_barrier
	ds_read_b128 v[32:35], v31
	ds_read_b128 v[36:39], v31 offset:2560
	ds_read_b128 v[40:43], v31 offset:5120
	ds_read_b128 v[44:47], v31 offset:7680
	ds_read_b128 v[48:51], v84 offset:40960
	ds_read_b128 v[52:55], v84 offset:43520
	ds_read_b128 v[80:83], v84 offset:46080
	ds_read_b128 v[84:87], v84 offset:48640
	ds_read_b128 v[88:91], v20 offset:64
	ds_read_b128 v[92:95], v20 offset:2624
	ds_read_b128 v[96:99], v20 offset:5184
	ds_read_b128 v[100:103], v20 offset:7744
	ds_read_b128 v[104:107], v21 offset:41024
	ds_read_b128 v[108:111], v21 offset:43584
	ds_read_b128 v[112:115], v21 offset:46144
	ds_read_b128 v[116:119], v21 offset:48704
	s_waitcnt lgkmcnt(11)
	v_mfma_f32_16x16x32_bf16 v[120:123], v[48:51], v[32:35], 0
	s_waitcnt vmcnt(5)
	ds_write_b128 v14, v[56:59] offset:61440
	s_waitcnt vmcnt(1)
	ds_write_b128 v15, v[72:75] offset:61440
	s_waitcnt lgkmcnt(12)
	v_mfma_f32_16x16x32_bf16 v[124:127], v[52:55], v[32:35], 0
	s_waitcnt lgkmcnt(11)
	v_mfma_f32_16x16x32_bf16 v[128:131], v[80:83], v[32:35], 0
	s_waitcnt lgkmcnt(10)
	v_mfma_f32_16x16x32_bf16 v[32:35], v[84:87], v[32:35], 0
	v_mfma_f32_16x16x32_bf16 v[56:59], v[48:51], v[36:39], 0
	ds_write_b128 v16, v[60:63] offset:61440
	s_waitcnt vmcnt(0)
	ds_write_b128 v17, v[76:79] offset:61440
	v_mfma_f32_16x16x32_bf16 v[72:75], v[52:55], v[36:39], 0
	v_mfma_f32_16x16x32_bf16 v[132:135], v[80:83], v[36:39], 0
	v_mfma_f32_16x16x32_bf16 v[36:39], v[84:87], v[36:39], 0
	v_mfma_f32_16x16x32_bf16 v[60:63], v[48:51], v[40:43], 0
	ds_write_b128 v22, v[64:67] offset:61440
	v_mfma_f32_16x16x32_bf16 v[76:79], v[52:55], v[40:43], 0
	v_mfma_f32_16x16x32_bf16 v[136:139], v[80:83], v[40:43], 0
	v_mfma_f32_16x16x32_bf16 v[40:43], v[84:87], v[40:43], 0
	v_mfma_f32_16x16x32_bf16 v[48:51], v[48:51], v[44:47], 0
	ds_write_b128 v23, v[68:71] offset:61440
	v_mfma_f32_16x16x32_bf16 v[52:55], v[52:55], v[44:47], 0
	v_mfma_f32_16x16x32_bf16 v[64:67], v[80:83], v[44:47], 0
	v_mfma_f32_16x16x32_bf16 v[44:47], v[84:87], v[44:47], 0
	s_waitcnt lgkmcnt(0)
	s_barrier
;     ...
;     G_MFMA_ST(fa0, fb0, ra1, rb1, 1);
;     __syncthreads();
;     G_READ(fa0, fb0, 1, 0);
;     __builtin_amdgcn_sched_barrier(0);
;     G_MFMA(fa1, fb1);
;     __builtin_amdgcn_sched_barrier(0);
;     G_READ(fa1, fb1, 1, 32);
;     if (k0 + 192 < K) G_LOAD(ra1, rb1, k0 + 192);
;     __builtin_amdgcn_sched_barrier(0);
;     if (k0 + 128 < K) {
;       G_MFMA_ST(fa0, fb0, ra0, rb0, 0);
;       __syncthreads();
;       G_READ(fa0, fb0, 0, 0);
;     } else {
;       G_MFMA(fa0, fb0);
;     }
;     __builtin_amdgcn_sched_barrier(0);
;     G_MFMA(fa1, fb1);
;     __builtin_amdgcn_sched_barrier(0);
	ds_read_b128 v[68:71], v31 offset:61440
	ds_read_b128 v[80:83], v31 offset:64000
	ds_read_b128 v[84:87], v24 offset:5120
	ds_read_b128 v[140:143], v24 offset:7680
	ds_read_b128 v[144:147], v25
	ds_read_b128 v[152:155], v25 offset:2560
	ds_read_b128 v[156:159], v25 offset:5120
	ds_read_b128 v[174:177], v25 offset:7680
	v_mfma_f32_16x16x32_bf16 v[120:123], v[104:107], v[88:91], v[120:123]
	v_mfma_f32_16x16x32_bf16 v[124:127], v[108:111], v[88:91], v[124:127]
	v_mfma_f32_16x16x32_bf16 v[128:131], v[112:115], v[88:91], v[128:131]
	v_mfma_f32_16x16x32_bf16 v[32:35], v[116:119], v[88:91], v[32:35]
	v_mfma_f32_16x16x32_bf16 v[56:59], v[104:107], v[92:95], v[56:59]
	v_mfma_f32_16x16x32_bf16 v[72:75], v[108:111], v[92:95], v[72:75]
	v_mfma_f32_16x16x32_bf16 v[88:91], v[112:115], v[92:95], v[132:135]
	v_mfma_f32_16x16x32_bf16 v[36:39], v[116:119], v[92:95], v[36:39]
	v_mfma_f32_16x16x32_bf16 v[60:63], v[104:107], v[96:99], v[60:63]
	v_mfma_f32_16x16x32_bf16 v[76:79], v[108:111], v[96:99], v[76:79]
	v_mfma_f32_16x16x32_bf16 v[92:95], v[112:115], v[96:99], v[136:139]
	v_mfma_f32_16x16x32_bf16 v[40:43], v[116:119], v[96:99], v[40:43]
	v_mfma_f32_16x16x32_bf16 v[48:51], v[104:107], v[100:103], v[48:51]
	v_mfma_f32_16x16x32_bf16 v[52:55], v[108:111], v[100:103], v[52:55]
	v_mfma_f32_16x16x32_bf16 v[64:67], v[112:115], v[100:103], v[64:67]
	v_mfma_f32_16x16x32_bf16 v[44:47], v[116:119], v[100:103], v[44:47]
	v_add_u32_e32 v31, v18, v10
	ds_read_b128 v[96:99], v20 offset:61504
	ds_read_b128 v[100:103], v20 offset:64064
	ds_read_b128 v[104:107], v26 offset:64
	ds_read_b128 v[108:111], v27 offset:64
	ds_read_b128 v[112:115], v31 offset:64
	ds_read_b128 v[116:119], v28 offset:64
	ds_read_b128 v[132:135], v29 offset:64
	ds_read_b128 v[136:139], v30 offset:64
	s_waitcnt lgkmcnt(11)
	v_mfma_f32_16x16x32_bf16 v[120:123], v[144:147], v[68:71], v[120:123]
	s_waitcnt lgkmcnt(10)
	v_mfma_f32_16x16x32_bf16 v[124:127], v[152:155], v[68:71], v[124:127]
	s_waitcnt lgkmcnt(9)
	v_mfma_f32_16x16x32_bf16 v[128:131], v[156:159], v[68:71], v[128:131]
	s_waitcnt lgkmcnt(8)
	v_mfma_f32_16x16x32_bf16 v[32:35], v[174:177], v[68:71], v[32:35]
	v_mfma_f32_16x16x32_bf16 v[56:59], v[144:147], v[80:83], v[56:59]
	v_mfma_f32_16x16x32_bf16 v[68:71], v[152:155], v[80:83], v[72:75]
	v_mfma_f32_16x16x32_bf16 v[72:75], v[156:159], v[80:83], v[88:91]
	v_mfma_f32_16x16x32_bf16 v[36:39], v[174:177], v[80:83], v[36:39]
	v_mfma_f32_16x16x32_bf16 v[60:63], v[144:147], v[84:87], v[60:63]
	v_mfma_f32_16x16x32_bf16 v[76:79], v[152:155], v[84:87], v[76:79]
	v_mfma_f32_16x16x32_bf16 v[80:83], v[156:159], v[84:87], v[92:95]
	v_mfma_f32_16x16x32_bf16 v[40:43], v[174:177], v[84:87], v[40:43]
	v_mfma_f32_16x16x32_bf16 v[48:51], v[144:147], v[140:143], v[48:51]
	v_mfma_f32_16x16x32_bf16 v[52:55], v[152:155], v[140:143], v[52:55]
	v_mfma_f32_16x16x32_bf16 v[64:67], v[156:159], v[140:143], v[64:67]
	v_mfma_f32_16x16x32_bf16 v[44:47], v[174:177], v[140:143], v[44:47]
	s_waitcnt lgkmcnt(3)
	v_mfma_f32_16x16x32_bf16 v[84:87], v[112:115], v[96:99], v[120:123]
	s_waitcnt lgkmcnt(2)
	v_mfma_f32_16x16x32_bf16 v[88:91], v[116:119], v[96:99], v[124:127]
	s_waitcnt lgkmcnt(1)
	v_mfma_f32_16x16x32_bf16 v[92:95], v[132:135], v[96:99], v[128:131]
	s_waitcnt lgkmcnt(0)
;     ...
;       G_MFMA(fa0, fb0);
;     }
;     __builtin_amdgcn_sched_barrier(0);
;     G_MFMA(fa1, fb1);
;     __builtin_amdgcn_sched_barrier(0);
; template <int TN, bool NTS = false>
; __device__ __forceinline__ void store_tile_bf16(const f32x4 (&acc)[4][TN], bf16_t* __restrict__ dst, int ldd, bf16_t* sT,
;                                                 const int tidx) {
;   constexpr int BN = 32 * TN, TS = BN + 8, CPR = BN / 8;
;   const int lane = tidx & 63, w = tidx >> 6;
;   const int wm = w >> 1, wn = w & 1, l15 = lane & 15, quad = lane >> 4;
;   __syncthreads();
; #pragma unroll
;   for (int i = 0; i < 4; i++)
; #pragma unroll
;     for (int j = 0; j < TN; j++)
; #pragma unroll
;       for (int r = 0; r < 4; r++)
;         sT[(wm * 64 + i * 16 + quad * 4 + r) * TS + wn * TN * 16 + j * 16 + l15] = f2bf(acc[i][j][r]);
;   __syncthreads();
; #pragma unroll
;   for (int c = tidx; c < 256 * CPR; c += NT) {
;     int row = c / CPR, cc = c % CPR;
;     const u32x4 v_ = *(const u32x4*)(sT + row * TS + cc * 8);
;     if (NTS) __builtin_nontemporal_store(v_, (u32x4*)(dst + (size_t)row * ldd + cc * 8));
;     else *(u32x4*)(dst + (size_t)row * ldd + cc * 8) = v_;
;   }
	v_mfma_f32_16x16x32_bf16 v[32:35], v[136:139], v[96:99], v[32:35]
	v_mfma_f32_16x16x32_bf16 v[56:59], v[112:115], v[100:103], v[56:59]
	v_mfma_f32_16x16x32_bf16 v[68:71], v[116:119], v[100:103], v[68:71]
	v_mfma_f32_16x16x32_bf16 v[72:75], v[132:135], v[100:103], v[72:75]
	v_mfma_f32_16x16x32_bf16 v[36:39], v[136:139], v[100:103], v[36:39]
	v_mfma_f32_16x16x32_bf16 v[60:63], v[112:115], v[104:107], v[60:63]
	v_mfma_f32_16x16x32_bf16 v[76:79], v[116:119], v[104:107], v[76:79]
	v_mfma_f32_16x16x32_bf16 v[80:83], v[132:135], v[104:107], v[80:83]
	v_mfma_f32_16x16x32_bf16 v[40:43], v[136:139], v[104:107], v[40:43]
	v_mfma_f32_16x16x32_bf16 v[48:51], v[112:115], v[108:111], v[48:51]
	v_mfma_f32_16x16x32_bf16 v[52:55], v[116:119], v[108:111], v[52:55]
	v_mfma_f32_16x16x32_bf16 v[64:67], v[132:135], v[108:111], v[64:67]
	v_mfma_f32_16x16x32_bf16 v[44:47], v[136:139], v[108:111], v[44:47]
	s_ashr_i32 s15, s14, 31
	s_ashr_i32 s13, s12, 31
	s_lshl_b64 s[10:11], s[14:15], 25
	s_add_u32 s14, s50, s10
	s_addc_u32 s15, s51, s11
	s_lshl_b64 s[10:11], s[12:13], 18
	s_add_u32 s10, s14, s10
	s_addc_u32 s11, s15, s11
	s_add_u32 s12, s10, s18
	s_addc_u32 s13, s11, 0
	v_lshrrev_b32_e32 v96, 7, v150
	v_and_b32_e32 v97, 7, v150
	v_lshl_or_b32 v96, v96, 6, v97
	v_lshlrev_b32_e32 v96, 10, v96
	v_bfe_u32 v97, v150, 6, 1
	v_bfe_u32 v98, v150, 3, 1
	v_lshl_or_b32 v97, v97, 1, v98
	v_bfe_u32 v98, v150, 4, 2
	v_lshl_or_b32 v97, v97, 2, v98
	v_lshl_add_u32 v96, v97, 4, v96
	v_add_u32_e32 v97, 0x2000, v96
	v_cvt_pk_bf16_f32 v84, v84, v85
	v_cvt_pk_bf16_f32 v85, v86, v87
	v_cvt_pk_bf16_f32 v86, v88, v89
	v_cvt_pk_bf16_f32 v87, v90, v91
	v_cvt_pk_bf16_f32 v92, v92, v93
	v_cvt_pk_bf16_f32 v93, v94, v95
	v_cvt_pk_bf16_f32 v94, v32, v33
	v_cvt_pk_bf16_f32 v95, v34, v35
	v_mov_b32_e32 v88, v84
	v_mov_b32_e32 v89, v85
	v_mov_b32_e32 v90, v86
	v_mov_b32_e32 v91, v87
	v_mov_b32_dpp v84, v92 row_ror:8 row_mask:0xf bank_mask:0xc
	v_mov_b32_dpp v85, v93 row_ror:8 row_mask:0xf bank_mask:0xc
	v_mov_b32_dpp v86, v94 row_ror:8 row_mask:0xf bank_mask:0xc
	v_mov_b32_dpp v87, v95 row_ror:8 row_mask:0xf bank_mask:0xc
	v_mov_b32_dpp v92, v88 row_ror:8 row_mask:0xf bank_mask:0x3
	v_mov_b32_dpp v93, v89 row_ror:8 row_mask:0xf bank_mask:0x3
	v_mov_b32_dpp v94, v90 row_ror:8 row_mask:0xf bank_mask:0x3
	v_mov_b32_dpp v95, v91 row_ror:8 row_mask:0xf bank_mask:0x3
	global_store_dwordx4 v96, v[84:87], s[12:13]
	global_store_dwordx4 v97, v[92:95], s[12:13]
	s_add_u32 s12, s12, 0x4000
	s_addc_u32 s13, s13, 0
	v_cvt_pk_bf16_f32 v56, v56, v57
	v_cvt_pk_bf16_f32 v57, v58, v59
	v_cvt_pk_bf16_f32 v58, v68, v69
	v_cvt_pk_bf16_f32 v59, v70, v71
	v_cvt_pk_bf16_f32 v72, v72, v73
	v_cvt_pk_bf16_f32 v73, v74, v75
	v_cvt_pk_bf16_f32 v74, v36, v37
	v_cvt_pk_bf16_f32 v75, v38, v39
	v_mov_b32_e32 v68, v56
	v_mov_b32_e32 v69, v57
	v_mov_b32_e32 v70, v58
	v_mov_b32_e32 v71, v59
	v_mov_b32_dpp v56, v72 row_ror:8 row_mask:0xf bank_mask:0xc
	v_mov_b32_dpp v57, v73 row_ror:8 row_mask:0xf bank_mask:0xc
	v_mov_b32_dpp v58, v74 row_ror:8 row_mask:0xf bank_mask:0xc
	v_mov_b32_dpp v59, v75 row_ror:8 row_mask:0xf bank_mask:0xc
	v_mov_b32_dpp v72, v68 row_ror:8 row_mask:0xf bank_mask:0x3
	v_mov_b32_dpp v73, v69 row_ror:8 row_mask:0xf bank_mask:0x3
	v_mov_b32_dpp v74, v70 row_ror:8 row_mask:0xf bank_mask:0x3
	v_mov_b32_dpp v75, v71 row_ror:8 row_mask:0xf bank_mask:0x3
	global_store_dwordx4 v96, v[56:59], s[12:13]
	global_store_dwordx4 v97, v[72:75], s[12:13]
	s_add_u32 s12, s12, 0x4000
	s_addc_u32 s13, s13, 0
	v_cvt_pk_bf16_f32 v60, v60, v61
	v_cvt_pk_bf16_f32 v61, v62, v63
	v_cvt_pk_bf16_f32 v62, v76, v77
	v_cvt_pk_bf16_f32 v63, v78, v79
	v_cvt_pk_bf16_f32 v80, v80, v81
	v_cvt_pk_bf16_f32 v81, v82, v83
	v_cvt_pk_bf16_f32 v82, v40, v41
	v_cvt_pk_bf16_f32 v83, v42, v43
	v_mov_b32_e32 v76, v60
	v_mov_b32_e32 v77, v61
	v_mov_b32_e32 v78, v62
	v_mov_b32_e32 v79, v63
	v_mov_b32_dpp v60, v80 row_ror:8 row_mask:0xf bank_mask:0xc
	v_mov_b32_dpp v61, v81 row_ror:8 row_mask:0xf bank_mask:0xc
	v_mov_b32_dpp v62, v82 row_ror:8 row_mask:0xf bank_mask:0xc
	v_mov_b32_dpp v63, v83 row_ror:8 row_mask:0xf bank_mask:0xc
	v_mov_b32_dpp v80, v76 row_ror:8 row_mask:0xf bank_mask:0x3
	v_mov_b32_dpp v81, v77 row_ror:8 row_mask:0xf bank_mask:0x3
	v_mov_b32_dpp v82, v78 row_ror:8 row_mask:0xf bank_mask:0x3
	v_mov_b32_dpp v83, v79 row_ror:8 row_mask:0xf bank_mask:0x3
	global_store_dwordx4 v96, v[60:63], s[12:13]
	global_store_dwordx4 v97, v[80:83], s[12:13]
	s_add_u32 s12, s12, 0x4000
	s_addc_u32 s13, s13, 0
	v_cvt_pk_bf16_f32 v48, v48, v49
	v_cvt_pk_bf16_f32 v49, v50, v51
	v_cvt_pk_bf16_f32 v50, v52, v53
	v_cvt_pk_bf16_f32 v51, v54, v55
	v_cvt_pk_bf16_f32 v64, v64, v65
	v_cvt_pk_bf16_f32 v65, v66, v67
	v_cvt_pk_bf16_f32 v66, v44, v45
	v_cvt_pk_bf16_f32 v67, v46, v47
	v_mov_b32_e32 v52, v48
	v_mov_b32_e32 v53, v49
	v_mov_b32_e32 v54, v50
	v_mov_b32_e32 v55, v51
	v_mov_b32_dpp v48, v64 row_ror:8 row_mask:0xf bank_mask:0xc
	v_mov_b32_dpp v49, v65 row_ror:8 row_mask:0xf bank_mask:0xc
	v_mov_b32_dpp v50, v66 row_ror:8 row_mask:0xf bank_mask:0xc
	v_mov_b32_dpp v51, v67 row_ror:8 row_mask:0xf bank_mask:0xc
	v_mov_b32_dpp v64, v52 row_ror:8 row_mask:0xf bank_mask:0x3
	v_mov_b32_dpp v65, v53 row_ror:8 row_mask:0xf bank_mask:0x3
	v_mov_b32_dpp v66, v54 row_ror:8 row_mask:0xf bank_mask:0x3
	v_mov_b32_dpp v67, v55 row_ror:8 row_mask:0xf bank_mask:0x3
	global_store_dwordx4 v96, v[48:51], s[12:13]
	global_store_dwordx4 v97, v[64:67], s[12:13]
	s_branch .LBB0_388
